# indexer table entries preloaded once per workgroup with a scalar load instead of a per-item vector load
# baseline (speedup 1.0000x reference)
.LBB0_625:
	s_andn2_b64 vcc, exec, s[0:1]
	s_cbranch_vccnz .LBB0_696
	s_mov_b32 s0, -1
	v_writelane_b32 v253, s0, 19
	s_mov_b32 s5, 0
	v_mov_b32_e32 v137, 0
	v_writelane_b32 v253, s1, 20
	s_movk_i32 s87, 0x1088
	s_mov_b32 s10, 0x5040100
	v_mov_b32_e32 v153, 0x10001
	s_movk_i32 s94, 0x108
	s_mov_b32 s95, 0
	s_mul_i32 s0, s91, 10
	s_getpc_b64 s[2:3]
	s_add_u32 s2, s2, _ZL7idx_tab@rel32@lo+4
	s_addc_u32 s3, s3, _ZL7idx_tab@rel32@hi+12
	s_and_b32 s1, s0, -4
	s_add_u32 s2, s2, s1
	s_addc_u32 s3, s3, 0
	s_load_dwordx2 s[98:99], s[2:3], 0x0
	s_load_dword s100, s[2:3], 0x8
	s_bfe_u32 s101, s0, 0x10001
	s_waitcnt lgkmcnt(0)
	s_branch .LBB0_630

.LBB0_630:
	s_mul_i32 s0, s91, 5
	s_add_i32 s4, s95, s0
	s_add_i32 s0, s95, s101
	s_lshr_b32 s1, s0, 1
	s_cmp_eq_u32 s1, 0
	s_cselect_b32 s2, s98, s99
	s_cmp_eq_u32 s1, 2
	s_cselect_b32 s2, s100, s2
	s_and_b32 s0, s0, 1
	s_lshl_b32 s0, s0, 4
	s_lshr_b32 s0, s2, s0
	s_and_b32 s0, s0, 0xffff
	s_cmp_eq_u32 s0, 0xffff
	s_cbranch_scc1 .LBB0_629
	s_and_b32 s0, 0xffff, s0
	v_writelane_b32 v253, s4, 21
	s_and_b32 s1, s0, 63
	s_lshr_b32 s2, s0, 7
	s_lshr_b32 s0, s0, 5
	v_writelane_b32 v253, s5, 22
	s_and_b32 s3, s0, 2
	s_lshl_b32 s4, s1, 2
	s_cmp_eq_u32 s1, 32
	s_cselect_b64 s[0:1], -1, 0
	s_and_b64 vcc, s[0:1], exec
	s_cselect_b32 s0, 0, s4
	s_or_b32 s0, s0, s3
	v_mov_b32_e32 v0, v151
	v_add_lshl_u32 v1, s0, v150, 4
	s_mov_b64 s[0:1], -1
	s_cbranch_vccnz .LBB0_633
	v_and_b32_e32 v2, 0xffffffc0, v1
	s_lshl_b32 s3, s2, 11
	s_lshl_b32 s4, s2, 18
	v_add_u32_e32 v2, 64, v2
	s_mov_b64 s[0:1], 0
	v_mov_b32_e32 v136, s4
	v_mov_b32_e32 v3, s3
